# attention: first K/V pair loads issued before waiting on the Q loads at each unit start; bias max loads batched
# speedup vs baseline: 1.0106x; 1.0106x over previous
.LBB0_1051:
	s_or_b64 exec, exec, s[4:5]
	s_mov_b64 s[12:13], s[0:1]
	s_waitcnt lgkmcnt(0)
	s_barrier
	s_mov_b32 s17, s2
	s_load_dwordx2 s[8:9], s[12:13], 0xa0
	v_mbcnt_lo_u32_b32 v4, -1, 0
	v_mbcnt_hi_u32_b32 v4, -1, v4
	s_load_dwordx4 s[4:7], s[12:13], 0x68
	s_load_dwordx2 s[14:15], s[12:13], 0x50
	v_and_b32_e32 v0, 63, v4
	v_lshlrev_b32_e32 v1, 2, v0
	s_waitcnt lgkmcnt(0)
	global_load_dword v7, v1, s[4:5]
	global_load_dword v6, v1, s[14:15]
	s_ashr_i32 s18, s17, 4
	s_mul_i32 s4, s18, 0x201
	v_mov_b32_e32 v1, 0
	s_ashr_i32 s5, s4, 31
	v_add_u32_e32 v5, s33, v4
	v_lshl_add_u64 v[2:3], s[4:5], 0, v[0:1]
	v_readfirstlane_b32 s16, v5
	v_or_b32_e32 v8, 0xffffffc0, v0
	v_lshl_add_u64 v[2:3], v[2:3], 2, s[6:7]
	v_mov_b32_e32 v1, 0xf149f2ca
	s_mov_b64 s[12:13], 0
	s_mov_b64 s[14:15], 0x100
	s_movk_i32 s5, 0x1c0
	global_load_dword v9, v[2:3], off
	global_load_dword v10, v[2:3], off offset:256
	global_load_dword v11, v[2:3], off offset:512
	global_load_dword v12, v[2:3], off offset:768
	global_load_dword v13, v[2:3], off offset:1024
	global_load_dword v14, v[2:3], off offset:1280
	global_load_dword v15, v[2:3], off offset:1536
	global_load_dword v16, v[2:3], off offset:1792
	v_mov_b32_e32 v17, 0xf149f2ca
	v_cmp_eq_u32_e32 vcc, 0, v0
	s_and_saveexec_b64 s[12:13], vcc
	global_load_dword v17, v[2:3], off offset:2048
	s_or_b64 exec, exec, s[12:13]
	s_waitcnt vmcnt(0)
	v_max3_f32 v1, v9, v10, v11
	v_max3_f32 v1, v1, v12, v13
	v_max3_f32 v1, v1, v14, v15
	v_max3_f32 v1, v1, v16, v17
	v_max_f32_e32 v1, 0xf149f2ca, v1
.LBB0_1052:
	v_and_b32_e32 v2, 0x7fffffff, v7
	ds_swizzle_b32 v2, v2 offset:swizzle(SWAP,1)
	v_max_f32_e64 v3, |v7|, |v7|
	v_add_u32_e32 v10, 0x200, v5
	s_mov_b32 s5, 0x151d07eb
	s_movk_i32 s12, 0xff
	s_waitcnt lgkmcnt(0)
	v_max_f32_e32 v2, v2, v2
	v_max_f32_e32 v23, v3, v2
	v_mul_hi_i32 v2, v10, s5
	v_lshrrev_b32_e32 v3, 31, v2
	v_ashrrev_i32_e32 v2, 6, v2
	v_add_u32_e32 v2, v2, v3
	v_mul_i32_i24_e32 v3, 0x308, v2
	v_sub_u32_e32 v2, v2, v5
	v_add3_u32 v15, v2, v3, s12
	v_min_i32_e32 v2, 0x13f, v15
	s_movk_i32 s14, 0xff3e
	v_add_u32_e32 v2, 0xc1, v2
	v_cmp_lt_i32_e32 vcc, s14, v15
	v_add_u32_e32 v13, 0x400, v5
	s_movk_i32 s12, 0xfeff
	v_cndmask_b32_e32 v2, 0, v2, vcc
	v_add_u32_e32 v2, s4, v2
	v_ashrrev_i32_e32 v3, 31, v2
	v_lshl_add_u64 v[24:25], v[2:3], 2, s[6:7]
	v_mul_hi_i32 v2, v13, s5
	v_lshrrev_b32_e32 v3, 31, v2
	v_ashrrev_i32_e32 v2, 6, v2
	v_add_u32_e32 v2, v2, v3
	v_mul_i32_i24_e32 v3, 0x308, v2
	v_sub_u32_e32 v2, v2, v5
	v_add3_u32 v16, v2, v3, s12
	v_min_i32_e32 v2, 0x13f, v16
	v_add_u32_e32 v2, 0xc1, v2
	v_cmp_lt_i32_e32 vcc, s14, v16
	v_add_u32_e32 v11, 0x600, v5
	s_movk_i32 s12, 0xfcff
	v_cndmask_b32_e32 v2, 0, v2, vcc
	v_add_u32_e32 v2, s4, v2
	v_ashrrev_i32_e32 v3, 31, v2
	v_lshl_add_u64 v[26:27], v[2:3], 2, s[6:7]
	v_mul_hi_i32 v2, v11, s5
	v_lshrrev_b32_e32 v3, 31, v2
	v_ashrrev_i32_e32 v2, 6, v2
	v_add_u32_e32 v2, v2, v3
	v_mul_i32_i24_e32 v3, 0x308, v2
	v_sub_u32_e32 v2, v2, v5
	v_add3_u32 v14, v2, v3, s12
	v_min_i32_e32 v2, 0x13f, v14
	v_add_u32_e32 v2, 0xc1, v2
	v_cmp_lt_i32_e32 vcc, s14, v14
	v_add_u32_e32 v7, 0x800, v5
	s_movk_i32 s12, 0xfaff
	v_cndmask_b32_e32 v2, 0, v2, vcc
	v_add_u32_e32 v2, s4, v2
	v_ashrrev_i32_e32 v3, 31, v2
	v_lshl_add_u64 v[28:29], v[2:3], 2, s[6:7]
	v_mul_hi_i32 v2, v7, s5
	v_lshrrev_b32_e32 v3, 31, v2
	v_ashrrev_i32_e32 v2, 6, v2
	v_add_u32_e32 v2, v2, v3
	v_mul_i32_i24_e32 v3, 0x308, v2
	v_sub_u32_e32 v2, v2, v5
	v_add3_u32 v12, v2, v3, s12
	v_min_i32_e32 v2, 0x13f, v12
	v_add_u32_e32 v2, 0xc1, v2
	v_cmp_lt_i32_e32 vcc, s14, v12
	s_movk_i32 s12, 0xf8ff
	s_nop 0
	v_cndmask_b32_e32 v2, 0, v2, vcc
	v_add_u32_e32 v2, s4, v2
	v_ashrrev_i32_e32 v3, 31, v2
	v_lshl_add_u64 v[30:31], v[2:3], 2, s[6:7]
	v_add_u32_e32 v2, 0xa00, v5
	v_mul_hi_i32 v3, v2, s5
	v_lshrrev_b32_e32 v8, 31, v3
	v_ashrrev_i32_e32 v3, 6, v3
	v_add_u32_e32 v3, v3, v8
	v_mul_i32_i24_e32 v8, 0x308, v3
	v_sub_u32_e32 v3, v3, v5
	v_add3_u32 v8, v3, v8, s12
	v_min_i32_e32 v3, 0x13f, v8
	v_add_u32_e32 v3, 0xc1, v3
	v_cmp_lt_i32_e32 vcc, s14, v8
	s_movk_i32 s12, 0xf6ff
	s_barrier
	v_cndmask_b32_e32 v3, 0, v3, vcc
	v_add_u32_e32 v18, s4, v3
	v_add_u32_e32 v3, 0xc00, v5
	v_mul_hi_i32 v9, v3, s5
	v_lshrrev_b32_e32 v17, 31, v9
	v_ashrrev_i32_e32 v9, 6, v9
	v_add_u32_e32 v9, v9, v17
	v_mul_i32_i24_e32 v17, 0x308, v9
	v_sub_u32_e32 v9, v9, v5
	v_add3_u32 v9, v9, v17, s12
	v_min_i32_e32 v17, 0x13f, v9
	v_add_u32_e32 v17, 0xc1, v17
	v_cmp_lt_i32_e32 vcc, s14, v9
	v_ashrrev_i32_e32 v19, 31, v18
	v_lshl_add_u64 v[32:33], v[18:19], 2, s[6:7]
	v_cndmask_b32_e32 v17, 0, v17, vcc
	v_add_u32_e32 v18, s4, v17
	v_ashrrev_i32_e32 v19, 31, v18
	v_lshl_add_u64 v[34:35], v[18:19], 2, s[6:7]
	global_load_dword v22, v[24:25], off
	global_load_dword v21, v[26:27], off
	global_load_dword v20, v[28:29], off
	global_load_dword v19, v[30:31], off
	global_load_dword v18, v[32:33], off
	global_load_dword v17, v[34:35], off
	ds_swizzle_b32 v36, v23 offset:swizzle(SWAP,2)
	v_and_b32_e32 v25, 0x7fffffff, v6
	ds_swizzle_b32 v25, v25 offset:swizzle(SWAP,1)
	v_max_f32_e64 v6, |v6|, |v6|
	ds_swizzle_b32 v26, v1 offset:swizzle(SWAP,1)
	s_waitcnt lgkmcnt(2)
	v_max_f32_e32 v24, v36, v36
	v_max_f32_e32 v23, v23, v24
	ds_swizzle_b32 v24, v23 offset:swizzle(SWAP,4)
	v_max_f32_e32 v1, v1, v1
	s_waitcnt lgkmcnt(1)
	v_max_f32_e32 v26, v26, v26
	v_max_f32_e32 v1, v1, v26
	ds_swizzle_b32 v26, v1 offset:swizzle(SWAP,2)
	s_waitcnt lgkmcnt(1)
	v_max_f32_e32 v24, v24, v24
	v_max_f32_e32 v23, v23, v24
	ds_swizzle_b32 v24, v23 offset:swizzle(SWAP,8)
	s_movk_i32 s12, 0xc20
	s_waitcnt lgkmcnt(1)
	v_max_f32_e32 v26, v26, v26
	v_max_f32_e32 v1, v1, v26
	ds_swizzle_b32 v26, v1 offset:swizzle(SWAP,4)
	s_waitcnt lgkmcnt(1)
	v_max_f32_e32 v24, v24, v24
	v_max_f32_e32 v23, v23, v24
	ds_swizzle_b32 v24, v23 offset:swizzle(SWAP,16)
	s_mov_b32 s15, 0x3fb8aa3b
	s_waitcnt lgkmcnt(1)
	v_max_f32_e32 v26, v26, v26
	v_max_f32_e32 v1, v1, v26
	ds_swizzle_b32 v26, v1 offset:swizzle(SWAP,8)
	s_waitcnt lgkmcnt(1)
	v_max_f32_e32 v24, v24, v24
	v_max_f32_e32 v23, v23, v24
	v_max_f32_e32 v24, v25, v25
	v_max_f32_e32 v6, v6, v24
	ds_swizzle_b32 v24, v6 offset:swizzle(SWAP,2)
	v_mov_b32_e32 v25, v23
	s_nop 1
	v_permlane32_swap_b32_e32 v23, v25
	v_max_f32_e32 v25, v25, v25
	s_waitcnt lgkmcnt(0)
	v_max_f32_e32 v24, v24, v24
	v_max_f32_e32 v6, v6, v24
	ds_swizzle_b32 v24, v6 offset:swizzle(SWAP,4)
	v_max_f32_e32 v23, v23, v23
	v_max_f32_e32 v23, v23, v25
	v_max_f32_e32 v25, v26, v26
	v_max_f32_e32 v1, v1, v25
	s_waitcnt lgkmcnt(0)
	v_max_f32_e32 v24, v24, v24
	v_max_f32_e32 v6, v6, v24
	ds_swizzle_b32 v24, v6 offset:swizzle(SWAP,8)
	ds_swizzle_b32 v25, v1 offset:swizzle(SWAP,16)
	v_mul_f32_e32 v23, 0x410147ae, v23
	v_cmp_gt_i32_e32 vcc, s12, v5
	s_waitcnt lgkmcnt(1)
	v_max_f32_e32 v24, v24, v24
	v_max_f32_e32 v6, v6, v24
	ds_swizzle_b32 v24, v6 offset:swizzle(SWAP,16)
	s_waitcnt lgkmcnt(0)
	v_max_f32_e32 v24, v24, v24
	v_max_f32_e32 v6, v6, v24
	v_mov_b32_e32 v24, v6
	s_nop 1
	v_permlane32_swap_b32_e32 v6, v24
	v_max_f32_e32 v24, v24, v24
	v_max_f32_e32 v6, v6, v6
	v_max_f32_e32 v6, v6, v24
	v_max_f32_e32 v24, v25, v25
	v_max_f32_e32 v1, v1, v24
	v_mov_b32_e32 v24, v1
	s_nop 1
	v_permlane32_swap_b32_e32 v1, v24
	v_max_f32_e32 v24, v24, v24
	v_max_f32_e32 v1, v1, v1
	v_max_f32_e32 v1, v1, v24
	v_fmac_f32_e32 v1, v23, v6
	v_mul_f32_e32 v1, 0x3fb8aa3b, v1
	s_and_saveexec_b64 s[12:13], vcc
	s_cbranch_execz .LBB0_1055
	v_mul_hi_i32 v6, v5, s5
	v_lshrrev_b32_e32 v23, 31, v6
	v_ashrrev_i32_e32 v6, 6, v6
	v_add_u32_e32 v6, v6, v23
	v_mul_i32_i24_e32 v23, 0x308, v6
	v_sub_u32_e32 v6, v6, v5
	s_movk_i32 s5, 0x2ff
	v_add3_u32 v6, v6, v23, s5
	v_min_i32_e32 v23, 0x13f, v6
	v_add_u32_e32 v23, 0xc1, v23
	v_cmp_lt_i32_e32 vcc, s14, v6
	s_nop 1
	v_cndmask_b32_e32 v23, 0, v23, vcc
	v_add_u32_e32 v24, s4, v23
	v_ashrrev_i32_e32 v25, 31, v24
	v_lshl_add_u64 v[24:25], v[24:25], 2, s[6:7]
	global_load_dword v23, v[24:25], off
	s_movk_i32 s4, 0x280
	v_mov_b32_e32 v24, 0xff800000
	v_lshl_add_u32 v25, v5, 2, 0
	v_cmp_gt_u32_e32 vcc, s4, v6
	s_waitcnt vmcnt(0)
	v_fma_f32 v23, v23, s15, -v1
	v_cndmask_b32_e32 v6, v24, v23, vcc
	v_add_u32_e32 v23, 0x20400, v25
	ds_write_b32 v23, v6

.LBB0_1070:
	s_or_b32 s12, s16, s14
	s_lshl_b32 s13, s12, 2
	s_add_i32 s20, s13, s15
	s_add_i32 s21, s13, -8
	s_cmp_gt_u32 s12, 1
	s_cselect_b32 s12, s21, 0
	s_ashr_i32 s21, s20, 31
	s_lshl_b64 s[20:21], s[20:21], 17
	v_lshl_add_u64 v[138:139], v[136:137], 0, s[20:21]
	v_add_co_u32_e32 v8, vcc, s19, v138
	s_sub_i32 s13, s13, s12
	s_nop 0
	v_addc_co_u32_e32 v9, vcc, 0, v139, vcc
	global_load_dwordx4 v[0:3], v[138:139], off
	global_load_dwordx4 v[4:7], v[8:9], off
	v_add_co_u32_e32 v8, vcc, 0x8000, v138
	s_add_i32 s13, s13, 4
	s_nop 0
	v_addc_co_u32_e32 v9, vcc, 0, v139, vcc
	v_add_co_u32_e32 v12, vcc, 0xc000, v138
	global_load_dwordx4 v[8:11], v[8:9], off
	s_nop 0
	v_addc_co_u32_e32 v13, vcc, 0, v139, vcc
	global_load_dwordx4 v[12:15], v[12:13], off
	s_ashr_i32 s20, s13, 1
	s_cmp_lt_i32 s20, 1
	s_cbranch_scc1 .Latt_slow
	s_or_b32 s22, s12, 1
	s_ashr_i32 s23, s22, 31
	s_lshl_b64 s[22:23], s[22:23], 17
	s_ashr_i32 s13, s12, 31
	v_lshl_add_u64 v[32:33], v[130:131], 0, s[22:23]
	v_lshl_add_u64 v[34:35], v[128:129], 0, s[22:23]
	s_lshl_b64 s[22:23], s[12:13], 17
	global_load_dwordx4 v[112:115], v[32:33], off
	global_load_dwordx4 v[116:119], v[34:35], off
	v_lshl_add_u64 v[32:33], v[130:131], 0, s[22:23]
	v_lshl_add_u64 v[34:35], v[128:129], 0, s[22:23]
	global_load_dwordx4 v[120:123], v[32:33], off
	global_load_dwordx4 v[124:127], v[34:35], off
	s_waitcnt vmcnt(7)
	ds_write_b128 v175, v[0:3]
	s_waitcnt vmcnt(6)
	ds_write_b128 v175, v[4:7] offset:1152
	s_waitcnt vmcnt(5)
	ds_write_b128 v175, v[8:11] offset:2304
	s_waitcnt vmcnt(4)
	ds_write_b128 v175, v[12:15] offset:3456
	s_branch .Latt_join
.Latt_slow:
	s_waitcnt vmcnt(3)
	ds_write_b128 v175, v[0:3]
	s_waitcnt vmcnt(2)
	ds_write_b128 v175, v[4:7] offset:1152
	s_waitcnt vmcnt(1)
	ds_write_b128 v175, v[8:11] offset:2304
	s_waitcnt vmcnt(0)
	ds_write_b128 v175, v[12:15] offset:3456
	s_cbranch_scc1 .LBB0_1068
	s_or_b32 s22, s12, 1
	s_ashr_i32 s23, s22, 31
	s_lshl_b64 s[22:23], s[22:23], 17
	s_ashr_i32 s13, s12, 31
	v_lshl_add_u64 v[0:1], v[130:131], 0, s[22:23]
	v_lshl_add_u64 v[2:3], v[128:129], 0, s[22:23]
	s_lshl_b64 s[22:23], s[12:13], 17
	global_load_dwordx4 v[112:115], v[0:1], off
	global_load_dwordx4 v[116:119], v[2:3], off
	v_lshl_add_u64 v[0:1], v[130:131], 0, s[22:23]
	v_lshl_add_u64 v[2:3], v[128:129], 0, s[22:23]
	global_load_dwordx4 v[120:123], v[0:1], off
	global_load_dwordx4 v[124:127], v[2:3], off
.Latt_join:
	ds_read_b128 v[96:99], v176
	ds_read_b128 v[100:103], v176 offset:32
	ds_read_b128 v[104:107], v176 offset:64
	ds_read_b128 v[108:111], v176 offset:96
	s_lshl_b32 s21, s12, 6
	v_mov_b32_e32 v178, 0
	s_sub_i32 s13, s17, s12
	s_add_i32 s21, s18, s21
	s_mov_b32 s22, 0
	s_mov_b32 s23, 0
	v_mov_b32_e32 v0, 0
	v_mov_b32_e32 v1, v178
	v_mov_b32_e32 v2, v178
	v_mov_b32_e32 v3, v178
	v_mov_b32_e32 v4, v178
	v_mov_b32_e32 v5, v178
	v_mov_b32_e32 v6, v178
	v_mov_b32_e32 v7, v178
	v_mov_b32_e32 v8, v178
	v_mov_b32_e32 v9, v178
	v_mov_b32_e32 v10, v178
	v_mov_b32_e32 v11, v178
	v_mov_b32_e32 v12, v178
	v_mov_b32_e32 v13, v178
	v_mov_b32_e32 v14, v178
	v_mov_b32_e32 v15, v178
	v_mov_b32_e32 v16, 0
	v_mov_b32_e32 v17, v178
	v_mov_b32_e32 v18, v178
	v_mov_b32_e32 v19, v178
	v_mov_b32_e32 v20, v178
	v_mov_b32_e32 v21, v178
	v_mov_b32_e32 v22, v178
	v_mov_b32_e32 v23, v178
	v_mov_b32_e32 v24, v178
	v_mov_b32_e32 v25, v178
	v_mov_b32_e32 v26, v178
	v_mov_b32_e32 v27, v178
	v_mov_b32_e32 v28, v178
	v_mov_b32_e32 v29, v178
	v_mov_b32_e32 v30, v178
	v_mov_b32_e32 v31, v178
	s_branch .LBB0_1073
